# LN1 and LN2: the 128 sample rows (split-K slab sums) are spread one per pair of workgroups instead of all on 16 workgroups
# speedup vs baseline: 1.0080x; 1.0056x over previous
.LBB0_1569:
	s_cmp_lt_i32 s56, 8
	s_cselect_b64 s[4:5], -1, 0
	s_and_b64 s[0:1], s[4:5], s[0:1]
	s_andn2_b64 vcc, exec, s[0:1]
	s_cbranch_vccnz .LBB0_1598
	v_lshl_add_u32 v33, s2, 3, v167
	s_movk_i32 s3, 0x2100
	v_cmp_gt_i32_e32 vcc, s3, v33
	s_and_saveexec_b64 s[8:9], vcc
	s_cbranch_execz .LBB0_1597
	s_lshr_b32 s10, s2, 1
	s_lshl_b32 s11, s2, 3
	s_sub_i32 s11, s11, s10
	s_addk_i32 s11, 0x7f
	v_and_b32_e32 v0, 15, v33
	v_cmp_eq_u32_e32 vcc, 0, v0
	v_add_u32_e32 v33, s11, v167
	v_mov_b32_e32 v0, s10
	s_nop 0
	v_cndmask_b32_e32 v33, v33, v0, vcc
	v_readlane_b32 s36, v239, 49
	v_and_b32_e32 v32, 63, v166
	v_readlane_b32 s48, v239, 61
	v_readlane_b32 s49, v239, 62
	s_add_u32 s10, s94, 0x8b00000
	v_mov_b32_e32 v35, 0
	v_or_b32_e32 v36, 0x100, v32
	v_or_b32_e32 v38, 0x140, v32
	v_or_b32_e32 v40, 0x180, v32
	v_or_b32_e32 v42, 0x1c0, v32
	v_readlane_b32 s50, v239, 63
	v_readlane_b32 s51, v238, 0
	s_mov_b64 s[20:21], s[48:49]
	s_addc_u32 s11, s95, 0
	s_waitcnt vmcnt(0)
	v_or_b32_e32 v0, 64, v32
	v_or_b32_e32 v2, 0x80, v32
	v_or_b32_e32 v4, 0xc0, v32
	s_mov_b64 s[22:23], s[50:51]
	v_lshlrev_b32_e32 v14, 4, v36
	v_mov_b32_e32 v15, v35
	v_lshlrev_b32_e32 v16, 4, v38
	v_mov_b32_e32 v17, v35
	v_lshlrev_b32_e32 v18, 4, v40
	v_mov_b32_e32 v19, v35
	v_lshlrev_b32_e32 v20, 4, v42
	v_mov_b32_e32 v21, v35
	s_add_u32 s14, s94, 0x100000
	v_lshlrev_b32_e32 v6, 2, v32
	v_lshlrev_b32_e32 v34, 4, v32
	v_lshlrev_b32_e32 v8, 2, v0
	v_lshlrev_b32_e32 v10, 2, v2
	v_lshlrev_b32_e32 v12, 2, v4
	v_lshl_add_u64 v[48:49], s[20:21], 0, v[14:15]
	v_lshl_add_u64 v[50:51], s[22:23], 0, v[14:15]
	v_lshlrev_b32_e32 v14, 2, v36
	v_lshl_add_u64 v[52:53], s[20:21], 0, v[16:17]
	v_lshl_add_u64 v[54:55], s[22:23], 0, v[16:17]
	v_lshlrev_b32_e32 v16, 2, v38
	v_lshl_add_u64 v[56:57], s[20:21], 0, v[18:19]
	v_lshl_add_u64 v[58:59], s[22:23], 0, v[18:19]
	v_lshlrev_b32_e32 v18, 2, v40
	v_lshl_add_u64 v[60:61], s[20:21], 0, v[20:21]
	v_lshl_add_u64 v[62:63], s[22:23], 0, v[20:21]
	v_lshlrev_b32_e32 v20, 2, v42
	v_lshlrev_b32_e32 v66, 4, v0
	v_mbcnt_lo_u32_b32 v0, -1, 0
	s_mov_b64 s[12:13], 0x100000
	s_addc_u32 s15, s95, 0
	s_lshl_b32 s3, s33, 3
	s_movk_i32 s19, 0x80
	v_lshl_add_u64 v[44:45], s[20:21], 0, v[34:35]
	v_lshl_add_u64 v[46:47], s[22:23], 0, v[34:35]
	v_lshl_add_u64 v[64:65], s[10:11], 0, v[34:35]
	s_mov_b64 s[16:17], 0
	s_movk_i32 s26, 0x2080
	s_movk_i32 s27, 0x1fff
	s_mov_b32 s18, 0x3f9837f0
	v_lshlrev_b32_e32 v68, 4, v2
	v_lshlrev_b32_e32 v70, 4, v4
	s_mov_b64 s[20:21], 0x200000
	s_mov_b64 s[22:23], 0x300000
	s_mov_b32 s4, 0
	v_mov_b32_e32 v37, 0x3727c5ac
	s_mov_b32 s28, 0x800000
	s_movk_i32 s29, 0x7fff
	s_mov_b32 s30, 0xffff0000
	v_lshlrev_b32_e32 v34, 1, v6
	v_lshlrev_b32_e32 v72, 1, v8
	v_lshlrev_b32_e32 v74, 1, v10
	v_lshlrev_b32_e32 v76, 1, v12
	v_lshlrev_b32_e32 v78, 1, v14
	v_lshlrev_b32_e32 v80, 1, v16
	v_lshlrev_b32_e32 v82, 1, v18
	v_lshlrev_b32_e32 v84, 1, v20
	s_movk_i32 s31, 0x20ff
	v_mbcnt_hi_u32_b32 v39, -1, v0
	v_readlane_b32 s37, v239, 50
	v_readlane_b32 s38, v239, 51
	v_readlane_b32 s39, v239, 52
	v_readlane_b32 s40, v239, 53
	v_readlane_b32 s41, v239, 54
	v_readlane_b32 s42, v239, 55
	v_readlane_b32 s43, v239, 56
	v_readlane_b32 s44, v239, 57
	v_readlane_b32 s45, v239, 58
	v_readlane_b32 s46, v239, 59
	v_readlane_b32 s47, v239, 60
	s_branch .LBB0_1573

.LBB0_1573:
	v_mov_b32_e32 v96, v33
	v_cmp_gt_i32_e32 vcc, s26, v96
	s_and_saveexec_b64 s[6:7], vcc
	s_xor_b64 s[6:7], exec, s[6:7]
	s_cbranch_execz .LBB0_1595
	v_cmp_lt_i32_e32 vcc, s27, v96
	v_lshlrev_b32_e32 v94, 4, v32
	v_lshlrev_b32_e32 v92, 4, v36
	v_lshlrev_b32_e32 v90, 4, v38
	v_lshlrev_b32_e32 v88, 4, v40
	v_lshlrev_b32_e32 v86, 4, v42
	s_and_saveexec_b64 s[24:25], vcc
	s_xor_b64 s[24:25], exec, s[24:25]
	s_cbranch_execz .LBB0_1576
	v_add_u32_e32 v0, 0xffffe000, v96
	v_mov_b32_e32 v1, v35
	v_readlane_b32 s36, v239, 17
	v_lshlrev_b64 v[98:99], 13, v[0:1]
	v_readlane_b32 s38, v239, 19
	v_readlane_b32 s39, v239, 20
	v_mov_b32_e32 v95, v35
	v_mov_b32_e32 v93, v35
	v_lshl_add_u64 v[24:25], s[38:39], 0, v[98:99]
	v_mov_b32_e32 v91, v35
	v_mov_b32_e32 v89, v35
	v_mov_b32_e32 v87, v35
	v_lshl_add_u64 v[196:197], s[14:15], 0, v[98:99]
	v_lshl_add_u64 v[0:1], v[24:25], 0, v[94:95]
	v_lshl_add_u64 v[16:17], v[24:25], 0, v[92:93]
	v_lshl_add_u64 v[20:21], v[24:25], 0, v[90:91]
	v_lshl_add_u64 v[26:27], v[24:25], 0, v[88:89]
	v_lshl_add_u64 v[28:29], v[24:25], 0, v[86:87]
	v_lshl_add_u64 v[110:111], v[196:197], 0, v[94:95]
	v_lshl_add_u64 v[114:115], v[196:197], 0, v[92:93]
	v_lshl_add_u64 v[118:119], v[196:197], 0, v[90:91]
	v_lshl_add_u64 v[154:155], v[196:197], 0, s[12:13]
	v_mov_b32_e32 v67, v35
	v_mov_b32_e32 v69, v35
	v_mov_b32_e32 v71, v35
	global_load_dwordx4 v[12:15], v[0:1], off
	global_load_dwordx4 v[8:11], v[0:1], off offset:1024
	global_load_dwordx4 v[4:7], v[0:1], off offset:2048
	s_nop 0
	global_load_dwordx4 v[0:3], v[0:1], off offset:3072
	s_nop 0
	global_load_dwordx4 v[16:19], v[16:17], off
	s_nop 0
	global_load_dwordx4 v[20:23], v[20:21], off
	s_nop 0
	global_load_dwordx4 v[24:27], v[26:27], off
	s_nop 0
	global_load_dwordx4 v[28:31], v[28:29], off
	s_nop 0
	global_load_dwordx4 v[98:101], v[110:111], off
	global_load_dwordx4 v[102:105], v[110:111], off offset:1024
	global_load_dwordx4 v[106:109], v[110:111], off offset:2048
	s_nop 0
	global_load_dwordx4 v[110:113], v[110:111], off offset:3072
	s_nop 0
	global_load_dwordx4 v[114:117], v[114:115], off
	s_nop 0
	global_load_dwordx4 v[118:121], v[118:119], off
	v_lshl_add_u64 v[122:123], v[196:197], 0, v[88:89]
	v_lshl_add_u64 v[126:127], v[196:197], 0, v[86:87]
	v_lshl_add_u64 v[130:131], v[154:155], 0, v[94:95]
	v_lshl_add_u64 v[134:135], v[154:155], 0, v[66:67]
	v_lshl_add_u64 v[138:139], v[154:155], 0, v[68:69]
	v_lshl_add_u64 v[142:143], v[154:155], 0, v[70:71]
	v_lshl_add_u64 v[146:147], v[154:155], 0, v[92:93]
	v_lshl_add_u64 v[150:151], v[154:155], 0, v[90:91]
	v_lshl_add_u64 v[188:189], v[196:197], 0, s[20:21]
	global_load_dwordx4 v[122:125], v[122:123], off
	s_nop 0
	global_load_dwordx4 v[126:129], v[126:127], off
	s_nop 0
	global_load_dwordx4 v[130:133], v[130:131], off
	s_nop 0
	global_load_dwordx4 v[134:137], v[134:135], off
	s_nop 0
	global_load_dwordx4 v[138:141], v[138:139], off
	s_nop 0
	global_load_dwordx4 v[142:145], v[142:143], off
	s_nop 0
	global_load_dwordx4 v[146:149], v[146:147], off
	s_nop 0
	global_load_dwordx4 v[150:153], v[150:151], off
	v_lshl_add_u64 v[156:157], v[154:155], 0, v[88:89]
	v_lshl_add_u64 v[158:159], v[154:155], 0, v[86:87]
	v_lshl_add_u64 v[162:163], v[188:189], 0, v[94:95]
	v_lshl_add_u64 v[168:169], v[188:189], 0, v[66:67]
	v_lshl_add_u64 v[172:173], v[188:189], 0, v[68:69]
	v_lshl_add_u64 v[176:177], v[188:189], 0, v[70:71]
	v_lshl_add_u64 v[180:181], v[188:189], 0, v[92:93]
	v_lshl_add_u64 v[184:185], v[188:189], 0, v[90:91]
	v_lshl_add_u64 v[224:225], v[196:197], 0, s[22:23]
	global_load_dwordx4 v[154:157], v[156:157], off
	s_nop 0
	global_load_dwordx4 v[158:161], v[158:159], off
	s_nop 0
	global_load_dwordx4 v[162:165], v[162:163], off
	s_nop 0
	global_load_dwordx4 v[168:171], v[168:169], off
	s_nop 0
	global_load_dwordx4 v[172:175], v[172:173], off
	s_nop 0
	global_load_dwordx4 v[176:179], v[176:177], off
	s_nop 0
	global_load_dwordx4 v[180:183], v[180:181], off
	s_nop 0
	global_load_dwordx4 v[184:187], v[184:185], off
	v_lshl_add_u64 v[190:191], v[188:189], 0, v[88:89]
	v_lshl_add_u64 v[192:193], v[188:189], 0, v[86:87]
	v_lshl_add_u64 v[196:197], v[224:225], 0, v[94:95]
	v_lshl_add_u64 v[200:201], v[224:225], 0, v[66:67]
	v_lshl_add_u64 v[204:205], v[224:225], 0, v[68:69]
	v_lshl_add_u64 v[212:213], v[224:225], 0, v[92:93]
	v_lshl_add_u64 v[216:217], v[224:225], 0, v[90:91]
	global_load_dwordx4 v[188:191], v[190:191], off
	s_nop 0
	global_load_dwordx4 v[192:195], v[192:193], off
	v_lshl_add_u64 v[208:209], v[224:225], 0, v[70:71]
	global_load_dwordx4 v[196:199], v[196:197], off
	v_lshl_add_u64 v[220:221], v[224:225], 0, v[88:89]
	global_load_dwordx4 v[200:203], v[200:201], off
	v_lshl_add_u64 v[224:225], v[224:225], 0, v[86:87]
	global_load_dwordx4 v[204:207], v[204:205], off
	v_readlane_b32 s37, v239, 18
	global_load_dwordx4 v[212:215], v[212:213], off
	v_readlane_b32 s40, v239, 21
	global_load_dwordx4 v[216:219], v[216:217], off
	v_readlane_b32 s41, v239, 22
	global_load_dwordx4 v[208:211], v[208:209], off
	v_readlane_b32 s42, v239, 23
	global_load_dwordx4 v[220:223], v[220:221], off
	v_readlane_b32 s43, v239, 24
	global_load_dwordx4 v[224:227], v[224:225], off
	v_readlane_b32 s44, v239, 25
	v_readlane_b32 s45, v239, 26
	v_readlane_b32 s46, v239, 27
	v_readlane_b32 s47, v239, 28
	v_readlane_b32 s48, v239, 29
	v_readlane_b32 s49, v239, 30
	v_readlane_b32 s50, v239, 31
	v_readlane_b32 s51, v239, 32
	s_waitcnt vmcnt(31)
	v_pk_fma_f32 v[14:15], v[14:15], s[18:19], v[100:101] op_sel_hi:[1,0,1]
	v_pk_fma_f32 v[12:13], v[12:13], s[18:19], v[98:99] op_sel_hi:[1,0,1]
	s_waitcnt vmcnt(30)
	v_pk_fma_f32 v[10:11], v[10:11], s[18:19], v[104:105] op_sel_hi:[1,0,1]
	v_pk_fma_f32 v[8:9], v[8:9], s[18:19], v[102:103] op_sel_hi:[1,0,1]
	s_waitcnt vmcnt(29)
	v_pk_fma_f32 v[6:7], v[6:7], s[18:19], v[108:109] op_sel_hi:[1,0,1]
	v_pk_fma_f32 v[4:5], v[4:5], s[18:19], v[106:107] op_sel_hi:[1,0,1]
	s_waitcnt vmcnt(27)
	v_pk_fma_f32 v[18:19], v[18:19], s[18:19], v[116:117] op_sel_hi:[1,0,1]
	v_pk_fma_f32 v[16:17], v[16:17], s[18:19], v[114:115] op_sel_hi:[1,0,1]
	s_waitcnt vmcnt(26)
	v_pk_fma_f32 v[22:23], v[22:23], s[18:19], v[120:121] op_sel_hi:[1,0,1]
	v_pk_fma_f32 v[20:21], v[20:21], s[18:19], v[118:119] op_sel_hi:[1,0,1]
	v_pk_fma_f32 v[2:3], v[2:3], s[18:19], v[112:113] op_sel_hi:[1,0,1]
	v_pk_fma_f32 v[0:1], v[0:1], s[18:19], v[110:111] op_sel_hi:[1,0,1]
	s_waitcnt vmcnt(25)
	v_pk_fma_f32 v[26:27], v[26:27], s[18:19], v[124:125] op_sel_hi:[1,0,1]
	v_pk_fma_f32 v[24:25], v[24:25], s[18:19], v[122:123] op_sel_hi:[1,0,1]
	s_waitcnt vmcnt(24)
	v_pk_fma_f32 v[30:31], v[30:31], s[18:19], v[128:129] op_sel_hi:[1,0,1]
	v_pk_fma_f32 v[28:29], v[28:29], s[18:19], v[126:127] op_sel_hi:[1,0,1]
	s_waitcnt vmcnt(23)
	v_pk_add_f32 v[14:15], v[14:15], v[132:133]
	v_pk_add_f32 v[12:13], v[12:13], v[130:131]
	s_waitcnt vmcnt(22)
	v_pk_add_f32 v[10:11], v[10:11], v[136:137]
	v_pk_add_f32 v[8:9], v[8:9], v[134:135]
	s_waitcnt vmcnt(21)
	v_pk_add_f32 v[6:7], v[6:7], v[140:141]
	v_pk_add_f32 v[4:5], v[4:5], v[138:139]
	s_waitcnt vmcnt(19)
	v_pk_add_f32 v[18:19], v[18:19], v[148:149]
	v_pk_add_f32 v[16:17], v[16:17], v[146:147]
	s_waitcnt vmcnt(18)
	v_pk_add_f32 v[22:23], v[22:23], v[152:153]
	v_pk_add_f32 v[20:21], v[20:21], v[150:151]
	v_pk_add_f32 v[2:3], v[2:3], v[144:145]
	v_pk_add_f32 v[0:1], v[0:1], v[142:143]
	s_waitcnt vmcnt(17)
	v_pk_add_f32 v[26:27], v[26:27], v[156:157]
	v_pk_add_f32 v[24:25], v[24:25], v[154:155]
	s_waitcnt vmcnt(16)
	v_pk_add_f32 v[30:31], v[30:31], v[160:161]
	v_pk_add_f32 v[28:29], v[28:29], v[158:159]
	s_waitcnt vmcnt(15)
	v_pk_add_f32 v[14:15], v[14:15], v[164:165]
	v_pk_add_f32 v[12:13], v[12:13], v[162:163]
	s_waitcnt vmcnt(14)
	v_pk_add_f32 v[10:11], v[10:11], v[170:171]
	v_pk_add_f32 v[8:9], v[8:9], v[168:169]
	s_waitcnt vmcnt(13)
	v_pk_add_f32 v[6:7], v[6:7], v[174:175]
	v_pk_add_f32 v[4:5], v[4:5], v[172:173]
	s_waitcnt vmcnt(11)
	v_pk_add_f32 v[98:99], v[18:19], v[182:183]
	v_pk_add_f32 v[100:101], v[16:17], v[180:181]
	s_waitcnt vmcnt(10)
	v_pk_add_f32 v[22:23], v[22:23], v[186:187]
	v_pk_add_f32 v[102:103], v[20:21], v[184:185]
	v_pk_add_f32 v[2:3], v[2:3], v[178:179]
	v_pk_add_f32 v[0:1], v[0:1], v[176:177]
	s_waitcnt vmcnt(9)
	v_pk_add_f32 v[26:27], v[26:27], v[190:191]
	v_pk_add_f32 v[24:25], v[24:25], v[188:189]
	s_waitcnt vmcnt(8)
	v_pk_add_f32 v[30:31], v[30:31], v[194:195]
	v_pk_add_f32 v[28:29], v[28:29], v[192:193]
	s_waitcnt vmcnt(7)
	v_pk_add_f32 v[112:113], v[14:15], v[198:199]
	v_pk_add_f32 v[114:115], v[12:13], v[196:197]
	s_waitcnt vmcnt(6)
	v_pk_add_f32 v[106:107], v[10:11], v[202:203]
	v_pk_add_f32 v[108:109], v[8:9], v[200:201]
	s_waitcnt vmcnt(5)
	v_pk_add_f32 v[20:21], v[6:7], v[206:207]
	v_pk_add_f32 v[10:11], v[4:5], v[204:205]
	s_waitcnt vmcnt(4)
	v_pk_add_f32 v[14:15], v[98:99], v[214:215]
	v_pk_add_f32 v[12:13], v[100:101], v[212:213]
	s_waitcnt vmcnt(3)
	v_pk_add_f32 v[8:9], v[22:23], v[218:219]
	v_pk_add_f32 v[22:23], v[102:103], v[216:217]
	s_waitcnt vmcnt(2)
	v_pk_add_f32 v[18:19], v[2:3], v[210:211]
	v_pk_add_f32 v[16:17], v[0:1], v[208:209]
	s_waitcnt vmcnt(1)
	v_pk_add_f32 v[6:7], v[26:27], v[222:223]
	v_pk_add_f32 v[4:5], v[24:25], v[220:221]
	s_waitcnt vmcnt(0)
	v_pk_add_f32 v[2:3], v[30:31], v[226:227]
	v_pk_add_f32 v[0:1], v[28:29], v[224:225]
	v_add_u32_e32 v196, 0xffffe000, v96
	v_mov_b32_e32 v197, 0
	v_lshlrev_b64 v[196:197], 13, v[196:197]
	v_lshl_add_u64 v[196:197], s[14:15], 0, v[196:197]
	v_lshl_add_u64 v[196:197], v[196:197], 0, v[94:95]
	s_mov_b32 vcc_lo, 0x400000
	s_mov_b32 vcc_hi, 0
	v_lshl_add_u64 v[198:199], v[196:197], 0, vcc
	s_mov_b32 vcc_lo, 0x401000
	v_lshl_add_u64 v[200:201], v[196:197], 0, vcc
	global_load_dwordx4 v[128:131], v[198:199], off
	global_load_dwordx4 v[132:135], v[198:199], off offset:1024
	global_load_dwordx4 v[136:139], v[198:199], off offset:2048
	global_load_dwordx4 v[140:143], v[198:199], off offset:3072
	global_load_dwordx4 v[144:147], v[200:201], off
	global_load_dwordx4 v[148:151], v[200:201], off offset:1024
	global_load_dwordx4 v[152:155], v[200:201], off offset:2048
	global_load_dwordx4 v[156:159], v[200:201], off offset:3072
	s_mov_b32 vcc_lo, 0x500000
	s_mov_b32 vcc_hi, 0
	v_lshl_add_u64 v[198:199], v[196:197], 0, vcc
	s_mov_b32 vcc_lo, 0x501000
	v_lshl_add_u64 v[200:201], v[196:197], 0, vcc
	global_load_dwordx4 v[160:163], v[198:199], off
	global_load_dwordx4 v[168:171], v[198:199], off offset:1024
	global_load_dwordx4 v[172:175], v[198:199], off offset:2048
	global_load_dwordx4 v[176:179], v[198:199], off offset:3072
	global_load_dwordx4 v[180:183], v[200:201], off
	global_load_dwordx4 v[184:187], v[200:201], off offset:1024
	global_load_dwordx4 v[188:191], v[200:201], off offset:2048
	global_load_dwordx4 v[192:195], v[200:201], off offset:3072
	s_waitcnt vmcnt(15)
	v_pk_add_f32 v[114:115], v[114:115], v[128:129]
	v_pk_add_f32 v[112:113], v[112:113], v[130:131]
	s_waitcnt vmcnt(14)
	v_pk_add_f32 v[108:109], v[108:109], v[132:133]
	v_pk_add_f32 v[106:107], v[106:107], v[134:135]
	s_waitcnt vmcnt(13)
	v_pk_add_f32 v[10:11], v[10:11], v[136:137]
	v_pk_add_f32 v[20:21], v[20:21], v[138:139]
	s_waitcnt vmcnt(12)
	v_pk_add_f32 v[16:17], v[16:17], v[140:141]
	v_pk_add_f32 v[18:19], v[18:19], v[142:143]
	s_waitcnt vmcnt(11)
	v_pk_add_f32 v[12:13], v[12:13], v[144:145]
	v_pk_add_f32 v[14:15], v[14:15], v[146:147]
	s_waitcnt vmcnt(10)
	v_pk_add_f32 v[22:23], v[22:23], v[148:149]
	v_pk_add_f32 v[8:9], v[8:9], v[150:151]
	s_waitcnt vmcnt(9)
	v_pk_add_f32 v[4:5], v[4:5], v[152:153]
	v_pk_add_f32 v[6:7], v[6:7], v[154:155]
	s_waitcnt vmcnt(8)
	v_pk_add_f32 v[0:1], v[0:1], v[156:157]
	v_pk_add_f32 v[2:3], v[2:3], v[158:159]
	s_waitcnt vmcnt(7)
	v_pk_add_f32 v[114:115], v[114:115], v[160:161]
	v_pk_add_f32 v[112:113], v[112:113], v[162:163]
	s_waitcnt vmcnt(6)
	v_pk_add_f32 v[108:109], v[108:109], v[168:169]
	v_pk_add_f32 v[106:107], v[106:107], v[170:171]
	s_waitcnt vmcnt(5)
	v_pk_add_f32 v[10:11], v[10:11], v[172:173]
	v_pk_add_f32 v[20:21], v[20:21], v[174:175]
	s_waitcnt vmcnt(4)
	v_pk_add_f32 v[16:17], v[16:17], v[176:177]
	v_pk_add_f32 v[18:19], v[18:19], v[178:179]
	s_waitcnt vmcnt(3)
	v_pk_add_f32 v[12:13], v[12:13], v[180:181]
	v_pk_add_f32 v[14:15], v[14:15], v[182:183]
	s_waitcnt vmcnt(2)
	v_pk_add_f32 v[22:23], v[22:23], v[184:185]
	v_pk_add_f32 v[8:9], v[8:9], v[186:187]
	s_waitcnt vmcnt(1)
	v_pk_add_f32 v[4:5], v[4:5], v[188:189]
	v_pk_add_f32 v[6:7], v[6:7], v[190:191]
	s_waitcnt vmcnt(0)
	v_pk_add_f32 v[0:1], v[0:1], v[192:193]
	v_pk_add_f32 v[2:3], v[2:3], v[194:195]
	s_mov_b32 vcc_lo, 0x600000
	s_mov_b32 vcc_hi, 0
	v_lshl_add_u64 v[198:199], v[196:197], 0, vcc
	s_mov_b32 vcc_lo, 0x601000
	v_lshl_add_u64 v[200:201], v[196:197], 0, vcc
	global_load_dwordx4 v[128:131], v[198:199], off
	global_load_dwordx4 v[132:135], v[198:199], off offset:1024
	global_load_dwordx4 v[136:139], v[198:199], off offset:2048
	global_load_dwordx4 v[140:143], v[198:199], off offset:3072
	global_load_dwordx4 v[144:147], v[200:201], off
	global_load_dwordx4 v[148:151], v[200:201], off offset:1024
	global_load_dwordx4 v[152:155], v[200:201], off offset:2048
	global_load_dwordx4 v[156:159], v[200:201], off offset:3072
	s_mov_b32 vcc_lo, 0x700000
	s_mov_b32 vcc_hi, 0
	v_lshl_add_u64 v[198:199], v[196:197], 0, vcc
	s_mov_b32 vcc_lo, 0x701000
	v_lshl_add_u64 v[200:201], v[196:197], 0, vcc
	global_load_dwordx4 v[160:163], v[198:199], off
	global_load_dwordx4 v[168:171], v[198:199], off offset:1024
	global_load_dwordx4 v[172:175], v[198:199], off offset:2048
	global_load_dwordx4 v[176:179], v[198:199], off offset:3072
	global_load_dwordx4 v[180:183], v[200:201], off
	global_load_dwordx4 v[184:187], v[200:201], off offset:1024
	global_load_dwordx4 v[188:191], v[200:201], off offset:2048
	global_load_dwordx4 v[192:195], v[200:201], off offset:3072
	s_waitcnt vmcnt(15)
	v_pk_add_f32 v[114:115], v[114:115], v[128:129]
	v_pk_add_f32 v[112:113], v[112:113], v[130:131]
	s_waitcnt vmcnt(14)
	v_pk_add_f32 v[108:109], v[108:109], v[132:133]
	v_pk_add_f32 v[106:107], v[106:107], v[134:135]
	s_waitcnt vmcnt(13)
	v_pk_add_f32 v[10:11], v[10:11], v[136:137]
	v_pk_add_f32 v[20:21], v[20:21], v[138:139]
	s_waitcnt vmcnt(12)
	v_pk_add_f32 v[16:17], v[16:17], v[140:141]
	v_pk_add_f32 v[18:19], v[18:19], v[142:143]
	s_waitcnt vmcnt(11)
	v_pk_add_f32 v[12:13], v[12:13], v[144:145]
	v_pk_add_f32 v[14:15], v[14:15], v[146:147]
	s_waitcnt vmcnt(10)
	v_pk_add_f32 v[22:23], v[22:23], v[148:149]
	v_pk_add_f32 v[8:9], v[8:9], v[150:151]
	s_waitcnt vmcnt(9)
	v_pk_add_f32 v[4:5], v[4:5], v[152:153]
	v_pk_add_f32 v[6:7], v[6:7], v[154:155]
	s_waitcnt vmcnt(8)
	v_pk_add_f32 v[0:1], v[0:1], v[156:157]
	v_pk_add_f32 v[2:3], v[2:3], v[158:159]
	s_waitcnt vmcnt(7)
	v_pk_add_f32 v[114:115], v[114:115], v[160:161]
	v_pk_add_f32 v[112:113], v[112:113], v[162:163]
	s_waitcnt vmcnt(6)
	v_pk_add_f32 v[108:109], v[108:109], v[168:169]
	v_pk_add_f32 v[106:107], v[106:107], v[170:171]
	s_waitcnt vmcnt(5)
	v_pk_add_f32 v[10:11], v[10:11], v[172:173]
	v_pk_add_f32 v[20:21], v[20:21], v[174:175]
	s_waitcnt vmcnt(4)
	v_pk_add_f32 v[16:17], v[16:17], v[176:177]
	v_pk_add_f32 v[18:19], v[18:19], v[178:179]
	s_waitcnt vmcnt(3)
	v_pk_add_f32 v[12:13], v[12:13], v[180:181]
	v_pk_add_f32 v[14:15], v[14:15], v[182:183]
	s_waitcnt vmcnt(2)
	v_pk_add_f32 v[22:23], v[22:23], v[184:185]
	v_pk_add_f32 v[8:9], v[8:9], v[186:187]
	s_waitcnt vmcnt(1)
	v_pk_add_f32 v[4:5], v[4:5], v[188:189]
	v_pk_add_f32 v[6:7], v[6:7], v[190:191]
	s_waitcnt vmcnt(0)
	v_pk_add_f32 v[0:1], v[0:1], v[192:193]
	v_pk_add_f32 v[2:3], v[2:3], v[194:195]
	v_mov_b32_e32 v101, v8
	v_mov_b32_e32 v100, v23
	v_mov_b32_e32 v8, v22
	v_mov_b32_e32 v102, v15
	v_mov_b32_e32 v104, v13
	v_mov_b32_e32 v111, v20
	v_mov_b32_e32 v110, v11
	v_mov_b32_e32 v20, v10
	v_mov_b32_e32 v26, v107
	v_mov_b32_e32 v24, v109
	v_mov_b32_e32 v27, v113
	v_mov_b32_e32 v107, v112
	v_mov_b32_e32 v25, v115
	v_mov_b32_e32 v109, v114

.LBB0_1819:
	s_cmp_lt_i32 s56, 11
	s_cselect_b64 s[4:5], -1, 0
	s_and_b64 s[0:1], s[4:5], s[0:1]
	s_andn2_b64 vcc, exec, s[0:1]
	s_cbranch_vccnz .LBB0_1829
	v_lshl_add_u32 v90, s2, 3, v167
	s_movk_i32 s0, 0x2100
	v_cmp_gt_i32_e32 vcc, s0, v90
	s_and_saveexec_b64 s[0:1], vcc
	s_cbranch_execz .LBB0_1829
	s_lshr_b32 s8, s2, 1
	s_lshl_b32 s9, s2, 3
	s_sub_i32 s9, s9, s8
	s_addk_i32 s9, 0x7f
	v_add_u32_e32 v90, s9, v167
	s_bitcmp0_b32 s2, 0
	s_cselect_b64 s[10:11], -1, 0
	v_cmp_eq_u32_e32 vcc, 0, v167
	v_mov_b32_e32 v0, s8
	s_and_b64 vcc, vcc, s[10:11]
	s_nop 1
	v_cndmask_b32_e32 v90, v90, v0, vcc
	v_readlane_b32 s8, v239, 0
	v_readlane_b32 s9, v239, 1
	v_readlane_b32 s10, v239, 2
	v_readlane_b32 s11, v239, 3
	v_readlane_b32 s12, v239, 4
	v_readlane_b32 s13, v239, 5
	s_waitcnt vmcnt(0)
	v_and_b32_e32 v0, 63, v166
	v_readlane_b32 s14, v239, 6
	v_readlane_b32 s15, v239, 7
	s_mov_b64 s[8:9], s[12:13]
	v_mov_b32_e32 v29, 0
	v_or_b32_e32 v8, 0x100, v0
	v_lshlrev_b32_e32 v28, 4, v0
	s_mov_b64 s[10:11], s[14:15]
	v_or_b32_e32 v10, 0x140, v0
	v_lshl_add_u64 v[30:31], s[8:9], 0, v[28:29]
	v_lshl_add_u64 v[32:33], s[10:11], 0, v[28:29]
	v_lshlrev_b32_e32 v28, 4, v8
	v_or_b32_e32 v12, 0x180, v0
	v_lshl_add_u64 v[34:35], s[8:9], 0, v[28:29]
	v_lshl_add_u64 v[36:37], s[10:11], 0, v[28:29]
	v_lshlrev_b32_e32 v28, 4, v10
	s_add_u32 s0, s92, 0x4000000
	v_or_b32_e32 v14, 0x1c0, v0
	v_lshl_add_u64 v[38:39], s[8:9], 0, v[28:29]
	v_lshl_add_u64 v[40:41], s[10:11], 0, v[28:29]
	v_lshlrev_b32_e32 v28, 4, v12
	s_addc_u32 s1, s93, 0
	v_lshl_add_u64 v[42:43], s[8:9], 0, v[28:29]
	v_lshl_add_u64 v[44:45], s[10:11], 0, v[28:29]
	v_lshlrev_b32_e32 v28, 4, v14
	s_add_u32 s2, s94, 0x800000
	v_or_b32_e32 v2, 64, v0
	v_or_b32_e32 v4, 0x80, v0
	v_or_b32_e32 v6, 0xc0, v0
	v_lshl_add_u64 v[46:47], s[8:9], 0, v[28:29]
	v_lshl_add_u64 v[48:49], s[10:11], 0, v[28:29]
	v_lshlrev_b32_e32 v28, 4, v0
	v_mbcnt_lo_u32_b32 v0, -1, 0
	s_addc_u32 s3, s95, 0
	s_lshl_b32 s7, s33, 3
	s_movk_i32 s26, 0x80
	s_mov_b64 s[4:5], 0
	s_movk_i32 s27, 0x2080
	s_movk_i32 s28, 0x1fff
	s_mov_b32 s6, 0x3f9837f0
	s_mov_b64 s[8:9], 0x100000
	v_lshlrev_b32_e32 v50, 4, v2
	v_lshlrev_b32_e32 v52, 4, v4
	v_lshlrev_b32_e32 v54, 4, v6
	s_mov_b64 s[10:11], 0x200000
	s_mov_b64 s[12:13], 0x300000
	s_mov_b64 s[14:15], 0x400000
	s_mov_b64 s[16:17], 0x500000
	s_mov_b64 s[18:19], 0x600000
	s_mov_b64 s[20:21], 0x700000
	v_mov_b32_e32 v91, 0x3727c5ac
	s_mov_b32 s29, 0x800000
	s_movk_i32 s30, 0x20ff
	v_lshlrev_b32_e32 v56, 4, v8
	v_lshlrev_b32_e32 v58, 4, v10
	v_lshlrev_b32_e32 v60, 4, v12
	v_lshlrev_b32_e32 v62, 4, v14
	v_mbcnt_hi_u32_b32 v92, -1, v0
	s_branch .LBB0_1824

.LBB0_1824:
	v_mov_b32_e32 v22, v90
	v_cmp_gt_i32_e32 vcc, s27, v22
	s_and_saveexec_b64 s[22:23], vcc
	s_cbranch_execz .LBB0_1823
	v_cmp_lt_i32_e32 vcc, s28, v22
	s_and_saveexec_b64 s[24:25], vcc
	s_xor_b64 s[24:25], exec, s[24:25]
	s_cbranch_execz .LBB0_1827
	v_add_u32_e32 v0, 0xffffe000, v22
	v_mov_b32_e32 v1, v29
	v_lshlrev_b64 v[0:1], 13, v[0:1]
	v_lshl_add_u64 v[2:3], s[0:1], 0, v[0:1]
	v_lshl_add_u64 v[16:17], v[2:3], 0, v[28:29]
	v_mov_b32_e32 v57, v29
	v_mov_b32_e32 v59, v29
	global_load_dwordx4 v[4:7], v[16:17], off
	global_load_dwordx4 v[8:11], v[16:17], off offset:1024
	global_load_dwordx4 v[12:15], v[16:17], off offset:2048
	global_load_dwordx4 v[24:27], v[16:17], off offset:3072
	v_lshl_add_u64 v[16:17], v[2:3], 0, v[56:57]
	v_lshl_add_u64 v[18:19], v[2:3], 0, v[58:59]
	global_load_dwordx4 v[64:67], v[16:17], off
	global_load_dwordx4 v[68:71], v[18:19], off
	v_mov_b32_e32 v61, v29
	v_lshl_add_u64 v[18:19], s[2:3], 0, v[0:1]
	v_lshl_add_u64 v[16:17], v[2:3], 0, v[60:61]
	v_mov_b32_e32 v63, v29
	v_lshl_add_u64 v[0:1], v[18:19], 0, v[28:29]
	v_lshl_add_u64 v[2:3], v[2:3], 0, v[62:63]
	global_load_dwordx4 v[72:75], v[16:17], off
	global_load_dwordx4 v[76:79], v[2:3], off
	global_load_dwordx4 v[80:83], v[0:1], off
	global_load_dwordx4 v[84:87], v[0:1], off offset:1024
	global_load_dwordx4 v[94:97], v[0:1], off offset:2048
	global_load_dwordx4 v[98:101], v[0:1], off offset:3072
	v_lshl_add_u64 v[0:1], v[18:19], 0, v[56:57]
	v_lshl_add_u64 v[2:3], v[18:19], 0, v[58:59]
	global_load_dwordx4 v[102:105], v[0:1], off
	global_load_dwordx4 v[106:109], v[2:3], off
	v_lshl_add_u64 v[0:1], v[18:19], 0, v[60:61]
	v_lshl_add_u64 v[2:3], v[18:19], 0, v[62:63]
	global_load_dwordx4 v[110:113], v[0:1], off
	global_load_dwordx4 v[114:117], v[2:3], off
	v_lshl_add_u64 v[0:1], v[18:19], 0, s[8:9]
	v_lshl_add_u64 v[2:3], v[0:1], 0, v[28:29]
	v_mov_b32_e32 v51, v29
	v_mov_b32_e32 v53, v29
	v_lshl_add_u64 v[16:17], v[0:1], 0, v[50:51]
	global_load_dwordx4 v[118:121], v[2:3], off
	global_load_dwordx4 v[122:125], v[16:17], off
	v_lshl_add_u64 v[2:3], v[0:1], 0, v[52:53]
	v_mov_b32_e32 v55, v29
	v_lshl_add_u64 v[16:17], v[0:1], 0, v[54:55]
	global_load_dwordx4 v[126:129], v[2:3], off
	global_load_dwordx4 v[130:133], v[16:17], off
	v_lshl_add_u64 v[2:3], v[0:1], 0, v[56:57]
	v_lshl_add_u64 v[16:17], v[0:1], 0, v[58:59]
	global_load_dwordx4 v[134:137], v[2:3], off
	global_load_dwordx4 v[138:141], v[16:17], off
	v_lshl_add_u64 v[2:3], v[0:1], 0, v[60:61]
	v_lshl_add_u64 v[0:1], v[0:1], 0, v[62:63]
	global_load_dwordx4 v[142:145], v[2:3], off
	global_load_dwordx4 v[146:149], v[0:1], off
	v_lshl_add_u64 v[0:1], v[18:19], 0, s[10:11]
	v_lshl_add_u64 v[2:3], v[0:1], 0, v[28:29]
	global_load_dwordx4 v[150:153], v[2:3], off
	v_lshl_add_u64 v[2:3], v[0:1], 0, v[50:51]
	global_load_dwordx4 v[154:157], v[2:3], off
	v_lshl_add_u64 v[2:3], v[0:1], 0, v[52:53]
	global_load_dwordx4 v[158:161], v[2:3], off
	v_lshl_add_u64 v[2:3], v[0:1], 0, v[54:55]
	global_load_dwordx4 v[162:165], v[2:3], off
	v_lshl_add_u64 v[2:3], v[0:1], 0, v[56:57]
	global_load_dwordx4 v[166:169], v[2:3], off
	v_lshl_add_u64 v[2:3], v[0:1], 0, v[58:59]
	global_load_dwordx4 v[170:173], v[2:3], off
	v_lshl_add_u64 v[2:3], v[0:1], 0, v[60:61]
	v_lshl_add_u64 v[0:1], v[0:1], 0, v[62:63]
	global_load_dwordx4 v[174:177], v[2:3], off
	v_lshl_add_u64 v[198:199], v[18:19], 0, s[18:19]
	global_load_dwordx4 v[0:3], v[0:1], off
	v_lshl_add_u64 v[178:179], v[198:199], 0, v[50:51]
	v_lshl_add_u64 v[182:183], v[198:199], 0, v[52:53]
	v_lshl_add_u64 v[186:187], v[198:199], 0, v[54:55]
	v_lshl_add_u64 v[190:191], v[198:199], 0, v[56:57]
	v_lshl_add_u64 v[194:195], v[198:199], 0, v[58:59]
	v_lshl_add_u64 v[200:201], v[198:199], 0, v[60:61]
	v_lshl_add_u64 v[202:203], v[198:199], 0, v[62:63]
	s_waitcnt vmcnt(23)
	v_pk_fma_f32 v[4:5], v[4:5], s[6:7], v[80:81] op_sel_hi:[1,0,1]
	v_pk_fma_f32 v[6:7], v[6:7], s[6:7], v[82:83] op_sel_hi:[1,0,1]
	s_waitcnt vmcnt(22)
	v_pk_fma_f32 v[10:11], v[10:11], s[6:7], v[86:87] op_sel_hi:[1,0,1]
	s_waitcnt vmcnt(20)
	v_pk_fma_f32 v[16:17], v[26:27], s[6:7], v[100:101] op_sel_hi:[1,0,1]
	v_pk_fma_f32 v[20:21], v[24:25], s[6:7], v[98:99] op_sel_hi:[1,0,1]
	s_waitcnt vmcnt(19)
	v_pk_fma_f32 v[24:25], v[66:67], s[6:7], v[104:105] op_sel_hi:[1,0,1]
	v_pk_fma_f32 v[26:27], v[64:65], s[6:7], v[102:103] op_sel_hi:[1,0,1]
	s_waitcnt vmcnt(18)
	v_pk_fma_f32 v[64:65], v[70:71], s[6:7], v[108:109] op_sel_hi:[1,0,1]
	v_pk_fma_f32 v[66:67], v[68:69], s[6:7], v[106:107] op_sel_hi:[1,0,1]
	s_waitcnt vmcnt(17)
	v_pk_fma_f32 v[68:69], v[74:75], s[6:7], v[112:113] op_sel_hi:[1,0,1]
	v_pk_fma_f32 v[70:71], v[72:73], s[6:7], v[110:111] op_sel_hi:[1,0,1]
	s_waitcnt vmcnt(16)
	v_pk_fma_f32 v[72:73], v[78:79], s[6:7], v[116:117] op_sel_hi:[1,0,1]
	v_pk_fma_f32 v[8:9], v[8:9], s[6:7], v[84:85] op_sel_hi:[1,0,1]
	v_pk_fma_f32 v[14:15], v[14:15], s[6:7], v[96:97] op_sel_hi:[1,0,1]
	v_pk_fma_f32 v[12:13], v[12:13], s[6:7], v[94:95] op_sel_hi:[1,0,1]
	v_pk_fma_f32 v[74:75], v[76:77], s[6:7], v[114:115] op_sel_hi:[1,0,1]
	s_waitcnt vmcnt(15)
	v_pk_add_f32 v[4:5], v[4:5], v[118:119]
	v_lshl_add_u64 v[102:103], v[18:19], 0, s[12:13]
	v_pk_add_f32 v[6:7], v[6:7], v[120:121]
	s_waitcnt vmcnt(12)
	v_pk_add_f32 v[76:77], v[20:21], v[130:131]
	v_pk_add_f32 v[10:11], v[10:11], v[124:125]
	s_waitcnt vmcnt(11)
	v_pk_add_f32 v[78:79], v[24:25], v[136:137]
	v_pk_add_f32 v[80:81], v[26:27], v[134:135]
	s_waitcnt vmcnt(10)
	v_pk_add_f32 v[82:83], v[64:65], v[140:141]
	v_pk_add_f32 v[84:85], v[66:67], v[138:139]
	s_waitcnt vmcnt(9)
	v_pk_add_f32 v[86:87], v[68:69], v[144:145]
	v_pk_add_f32 v[88:89], v[70:71], v[142:143]
	s_waitcnt vmcnt(8)
	v_pk_add_f32 v[94:95], v[72:73], v[148:149]
	v_lshl_add_u64 v[134:135], v[18:19], 0, s[14:15]
	v_pk_add_f32 v[8:9], v[8:9], v[122:123]
	v_pk_add_f32 v[14:15], v[14:15], v[128:129]
	v_pk_add_f32 v[12:13], v[12:13], v[126:127]
	v_pk_add_f32 v[16:17], v[16:17], v[132:133]
	v_pk_add_f32 v[20:21], v[74:75], v[146:147]
	s_waitcnt vmcnt(7)
	v_pk_add_f32 v[26:27], v[4:5], v[150:151]
	s_waitcnt vmcnt(4)
	v_pk_add_f32 v[74:75], v[76:77], v[162:163]
	s_waitcnt vmcnt(3)
	v_pk_add_f32 v[76:77], v[78:79], v[168:169]
	v_pk_add_f32 v[78:79], v[80:81], v[166:167]
	s_waitcnt vmcnt(2)
	v_pk_add_f32 v[80:81], v[82:83], v[172:173]
	v_pk_add_f32 v[82:83], v[84:85], v[170:171]
	v_lshl_add_u64 v[4:5], v[102:103], 0, v[50:51]
	s_waitcnt vmcnt(1)
	v_pk_add_f32 v[84:85], v[86:87], v[176:177]
	v_pk_add_f32 v[86:87], v[88:89], v[174:175]
	s_waitcnt vmcnt(0)
	v_pk_add_f32 v[88:89], v[94:95], v[2:3]
	v_lshl_add_u64 v[2:3], v[102:103], 0, v[28:29]
	v_lshl_add_u64 v[94:95], v[102:103], 0, v[52:53]
	v_lshl_add_u64 v[96:97], v[102:103], 0, v[54:55]
	v_lshl_add_u64 v[104:105], v[102:103], 0, v[56:57]
	v_lshl_add_u64 v[106:107], v[102:103], 0, v[58:59]
	v_lshl_add_u64 v[110:111], v[102:103], 0, v[60:61]
	v_lshl_add_u64 v[112:113], v[102:103], 0, v[62:63]
	v_lshl_add_u64 v[118:119], v[134:135], 0, v[28:29]
	v_pk_add_f32 v[24:25], v[6:7], v[152:153]
	v_pk_add_f32 v[64:65], v[10:11], v[156:157]
	v_pk_add_f32 v[66:67], v[8:9], v[154:155]
	v_pk_add_f32 v[68:69], v[14:15], v[160:161]
	v_pk_add_f32 v[70:71], v[12:13], v[158:159]
	v_pk_add_f32 v[72:73], v[16:17], v[164:165]
	global_load_dwordx4 v[6:9], v[2:3], off
	s_nop 0
	global_load_dwordx4 v[2:5], v[4:5], off
	s_nop 0
	global_load_dwordx4 v[14:17], v[94:95], off
	global_load_dwordx4 v[10:13], v[96:97], off
	s_nop 0
	global_load_dwordx4 v[94:97], v[104:105], off
	global_load_dwordx4 v[98:101], v[106:107], off
	s_nop 0
	global_load_dwordx4 v[102:105], v[110:111], off
	global_load_dwordx4 v[106:109], v[112:113], off
	v_lshl_add_u64 v[120:121], v[134:135], 0, v[50:51]
	global_load_dwordx4 v[110:113], v[118:119], off
	global_load_dwordx4 v[114:117], v[120:121], off
	v_lshl_add_u64 v[118:119], v[134:135], 0, v[52:53]
	v_lshl_add_u64 v[122:123], v[134:135], 0, v[54:55]
	v_lshl_add_u64 v[126:127], v[134:135], 0, v[56:57]
	v_lshl_add_u64 v[130:131], v[134:135], 0, v[58:59]
	v_lshl_add_u64 v[166:167], v[18:19], 0, s[16:17]
	global_load_dwordx4 v[118:121], v[118:119], off
	s_nop 0
	global_load_dwordx4 v[122:125], v[122:123], off
	s_nop 0
	global_load_dwordx4 v[126:129], v[126:127], off
	s_nop 0
	global_load_dwordx4 v[130:133], v[130:131], off
	v_lshl_add_u64 v[136:137], v[134:135], 0, v[60:61]
	v_lshl_add_u64 v[138:139], v[134:135], 0, v[62:63]
	v_lshl_add_u64 v[142:143], v[166:167], 0, v[28:29]
	v_lshl_add_u64 v[146:147], v[166:167], 0, v[50:51]
	v_lshl_add_u64 v[150:151], v[166:167], 0, v[52:53]
	v_lshl_add_u64 v[154:155], v[166:167], 0, v[54:55]
	v_lshl_add_u64 v[158:159], v[166:167], 0, v[56:57]
	v_lshl_add_u64 v[162:163], v[166:167], 0, v[58:59]
	global_load_dwordx4 v[134:137], v[136:137], off
	s_nop 0
	global_load_dwordx4 v[138:141], v[138:139], off
	s_nop 0
	global_load_dwordx4 v[142:145], v[142:143], off
	s_nop 0
	global_load_dwordx4 v[146:149], v[146:147], off
	s_nop 0
	global_load_dwordx4 v[150:153], v[150:151], off
	s_nop 0
	global_load_dwordx4 v[154:157], v[154:155], off
	s_nop 0
	global_load_dwordx4 v[158:161], v[158:159], off
	s_nop 0
	global_load_dwordx4 v[162:165], v[162:163], off
	v_lshl_add_u64 v[168:169], v[166:167], 0, v[60:61]
	v_lshl_add_u64 v[170:171], v[166:167], 0, v[62:63]
	v_lshl_add_u64 v[174:175], v[198:199], 0, v[28:29]
	v_lshl_add_u64 v[18:19], v[18:19], 0, s[20:21]
	global_load_dwordx4 v[166:169], v[168:169], off
	s_nop 0
	global_load_dwordx4 v[170:173], v[170:171], off
	s_nop 0
	global_load_dwordx4 v[174:177], v[174:175], off
	s_nop 0
	global_load_dwordx4 v[178:181], v[178:179], off
	s_nop 0
	global_load_dwordx4 v[182:185], v[182:183], off
	s_nop 0
	global_load_dwordx4 v[186:189], v[186:187], off
	s_nop 0
	global_load_dwordx4 v[190:193], v[190:191], off
	s_nop 0
	global_load_dwordx4 v[194:197], v[194:195], off
	v_lshl_add_u64 v[206:207], v[18:19], 0, v[28:29]
	v_lshl_add_u64 v[210:211], v[18:19], 0, v[50:51]
	v_lshl_add_u64 v[214:215], v[18:19], 0, v[52:53]
	v_lshl_add_u64 v[218:219], v[18:19], 0, v[54:55]
	v_lshl_add_u64 v[222:223], v[18:19], 0, v[56:57]
	v_lshl_add_u64 v[226:227], v[18:19], 0, v[58:59]
	global_load_dwordx4 v[198:201], v[200:201], off
	s_nop 0
	global_load_dwordx4 v[202:205], v[202:203], off
	v_lshl_add_u64 v[230:231], v[18:19], 0, v[60:61]
	global_load_dwordx4 v[206:209], v[206:207], off
	v_lshl_add_u64 v[18:19], v[18:19], 0, v[62:63]
	global_load_dwordx4 v[210:213], v[210:211], off
	v_pk_add_f32 v[0:1], v[20:21], v[0:1]
	global_load_dwordx4 v[214:217], v[214:215], off
	s_waitcnt vmcnt(34)
	v_pk_add_f32 v[8:9], v[24:25], v[8:9]
	global_load_dwordx4 v[218:221], v[218:219], off
	v_pk_add_f32 v[6:7], v[26:27], v[6:7]
	global_load_dwordx4 v[222:225], v[222:223], off
	s_waitcnt vmcnt(35)
	v_pk_add_f32 v[4:5], v[64:65], v[4:5]
	global_load_dwordx4 v[226:229], v[226:227], off
	v_pk_add_f32 v[2:3], v[66:67], v[2:3]
	global_load_dwordx4 v[230:233], v[230:231], off
	s_waitcnt vmcnt(36)
	v_pk_add_f32 v[16:17], v[68:69], v[16:17]
	global_load_dwordx4 v[234:237], v[18:19], off
	v_pk_add_f32 v[14:15], v[70:71], v[14:15]
	s_waitcnt vmcnt(36)
	v_pk_add_f32 v[12:13], v[72:73], v[12:13]
	v_pk_add_f32 v[10:11], v[74:75], v[10:11]
	s_waitcnt vmcnt(35)
	v_pk_add_f32 v[18:19], v[76:77], v[96:97]
	v_pk_add_f32 v[20:21], v[78:79], v[94:95]
	s_waitcnt vmcnt(34)
	v_pk_add_f32 v[24:25], v[80:81], v[100:101]
	v_pk_add_f32 v[26:27], v[82:83], v[98:99]
	s_waitcnt vmcnt(33)
	v_pk_add_f32 v[64:65], v[84:85], v[104:105]
	v_pk_add_f32 v[66:67], v[86:87], v[102:103]
	s_waitcnt vmcnt(32)
	v_pk_add_f32 v[68:69], v[88:89], v[108:109]
	v_pk_add_f32 v[0:1], v[0:1], v[106:107]
	s_waitcnt vmcnt(31)
	v_pk_add_f32 v[8:9], v[8:9], v[112:113]
	v_pk_add_f32 v[6:7], v[6:7], v[110:111]
	s_waitcnt vmcnt(30)
	v_pk_add_f32 v[4:5], v[4:5], v[116:117]
	v_pk_add_f32 v[2:3], v[2:3], v[114:115]
	s_waitcnt vmcnt(29)
	v_pk_add_f32 v[16:17], v[16:17], v[120:121]
	v_pk_add_f32 v[14:15], v[14:15], v[118:119]
	s_waitcnt vmcnt(28)
	v_pk_add_f32 v[12:13], v[12:13], v[124:125]
	v_pk_add_f32 v[10:11], v[10:11], v[122:123]
	s_waitcnt vmcnt(27)
	v_pk_add_f32 v[18:19], v[18:19], v[128:129]
	v_pk_add_f32 v[20:21], v[20:21], v[126:127]
	s_waitcnt vmcnt(26)
	v_pk_add_f32 v[24:25], v[24:25], v[132:133]
	v_pk_add_f32 v[26:27], v[26:27], v[130:131]
	s_waitcnt vmcnt(25)
	v_pk_add_f32 v[64:65], v[64:65], v[136:137]
	v_pk_add_f32 v[66:67], v[66:67], v[134:135]
	s_waitcnt vmcnt(24)
	v_pk_add_f32 v[68:69], v[68:69], v[140:141]
	v_pk_add_f32 v[0:1], v[0:1], v[138:139]
	s_waitcnt vmcnt(23)
	v_pk_add_f32 v[8:9], v[8:9], v[144:145]
	v_pk_add_f32 v[6:7], v[6:7], v[142:143]
	s_waitcnt vmcnt(22)
	v_pk_add_f32 v[4:5], v[4:5], v[148:149]
	v_pk_add_f32 v[2:3], v[2:3], v[146:147]
	s_waitcnt vmcnt(21)
	v_pk_add_f32 v[16:17], v[16:17], v[152:153]
	v_pk_add_f32 v[14:15], v[14:15], v[150:151]
	s_waitcnt vmcnt(20)
	v_pk_add_f32 v[12:13], v[12:13], v[156:157]
	v_pk_add_f32 v[10:11], v[10:11], v[154:155]
	s_waitcnt vmcnt(19)
	v_pk_add_f32 v[18:19], v[18:19], v[160:161]
	v_pk_add_f32 v[20:21], v[20:21], v[158:159]
	s_waitcnt vmcnt(18)
	v_pk_add_f32 v[24:25], v[24:25], v[164:165]
	v_pk_add_f32 v[26:27], v[26:27], v[162:163]
	s_waitcnt vmcnt(17)
	v_pk_add_f32 v[64:65], v[64:65], v[168:169]
	v_pk_add_f32 v[66:67], v[66:67], v[166:167]
	s_waitcnt vmcnt(16)
	v_pk_add_f32 v[68:69], v[68:69], v[172:173]
	v_pk_add_f32 v[0:1], v[0:1], v[170:171]
	s_waitcnt vmcnt(15)
	v_pk_add_f32 v[8:9], v[8:9], v[176:177]
	v_pk_add_f32 v[6:7], v[6:7], v[174:175]
	s_waitcnt vmcnt(14)
	v_pk_add_f32 v[4:5], v[4:5], v[180:181]
	v_pk_add_f32 v[2:3], v[2:3], v[178:179]
	s_waitcnt vmcnt(13)
	v_pk_add_f32 v[16:17], v[16:17], v[184:185]
	v_pk_add_f32 v[14:15], v[14:15], v[182:183]
	s_waitcnt vmcnt(12)
	v_pk_add_f32 v[12:13], v[12:13], v[188:189]
	v_pk_add_f32 v[10:11], v[10:11], v[186:187]
	s_waitcnt vmcnt(11)
	v_pk_add_f32 v[74:75], v[18:19], v[192:193]
	v_pk_add_f32 v[76:77], v[20:21], v[190:191]
	s_waitcnt vmcnt(10)
	v_pk_add_f32 v[24:25], v[24:25], v[196:197]
	v_pk_add_f32 v[26:27], v[26:27], v[194:195]
	s_waitcnt vmcnt(9)
	v_pk_add_f32 v[64:65], v[64:65], v[200:201]
	v_pk_add_f32 v[66:67], v[66:67], v[198:199]
	s_waitcnt vmcnt(8)
	v_pk_add_f32 v[68:69], v[68:69], v[204:205]
	v_pk_add_f32 v[78:79], v[0:1], v[202:203]
	s_waitcnt vmcnt(7)
	v_pk_add_f32 v[80:81], v[8:9], v[208:209]
	v_pk_add_f32 v[82:83], v[6:7], v[206:207]
	s_waitcnt vmcnt(6)
	v_pk_add_f32 v[70:71], v[4:5], v[212:213]
	v_pk_add_f32 v[72:73], v[2:3], v[210:211]
	s_waitcnt vmcnt(5)
	v_pk_add_f32 v[20:21], v[16:17], v[216:217]
	v_pk_add_f32 v[84:85], v[14:15], v[214:215]
	s_waitcnt vmcnt(4)
	v_pk_add_f32 v[18:19], v[12:13], v[220:221]
	v_pk_add_f32 v[16:17], v[10:11], v[218:219]
	s_waitcnt vmcnt(3)
	v_pk_add_f32 v[14:15], v[74:75], v[224:225]
	v_pk_add_f32 v[12:13], v[76:77], v[222:223]
	s_waitcnt vmcnt(2)
	v_pk_add_f32 v[8:9], v[24:25], v[228:229]
	v_pk_add_f32 v[10:11], v[26:27], v[226:227]
	s_waitcnt vmcnt(1)
	v_pk_add_f32 v[2:3], v[64:65], v[232:233]
	v_pk_add_f32 v[0:1], v[66:67], v[230:231]
	s_waitcnt vmcnt(0)
	v_pk_add_f32 v[6:7], v[68:69], v[236:237]
	v_pk_add_f32 v[4:5], v[78:79], v[234:235]
	v_add_u32_e32 v86, 0xffffe000, v22
	v_mov_b32_e32 v87, 0
	v_lshlrev_b64 v[86:87], 13, v[86:87]
	v_lshl_add_u64 v[86:87], s[2:3], 0, v[86:87]
	v_lshl_add_u64 v[86:87], v[86:87], 0, v[28:29]
	s_mov_b32 s40, 0x800000
	s_mov_b32 s41, 0
	v_lshl_add_u64 v[88:89], v[86:87], 0, s[40:41]
	s_mov_b32 s40, 0x801000
	v_lshl_add_u64 v[94:95], v[86:87], 0, s[40:41]
	global_load_dwordx4 v[96:99], v[88:89], off
	global_load_dwordx4 v[100:103], v[88:89], off offset:1024
	global_load_dwordx4 v[104:107], v[88:89], off offset:2048
	global_load_dwordx4 v[108:111], v[88:89], off offset:3072
	global_load_dwordx4 v[112:115], v[94:95], off
	global_load_dwordx4 v[116:119], v[94:95], off offset:1024
	global_load_dwordx4 v[120:123], v[94:95], off offset:2048
	global_load_dwordx4 v[124:127], v[94:95], off offset:3072
	s_mov_b32 s40, 0x900000
	s_mov_b32 s41, 0
	v_lshl_add_u64 v[88:89], v[86:87], 0, s[40:41]
	s_mov_b32 s40, 0x901000
	v_lshl_add_u64 v[94:95], v[86:87], 0, s[40:41]
	global_load_dwordx4 v[128:131], v[88:89], off
	global_load_dwordx4 v[132:135], v[88:89], off offset:1024
	global_load_dwordx4 v[136:139], v[88:89], off offset:2048
	global_load_dwordx4 v[140:143], v[88:89], off offset:3072
	global_load_dwordx4 v[144:147], v[94:95], off
	global_load_dwordx4 v[148:151], v[94:95], off offset:1024
	global_load_dwordx4 v[152:155], v[94:95], off offset:2048
	global_load_dwordx4 v[156:159], v[94:95], off offset:3072
	s_mov_b32 s40, 0xa00000
	s_mov_b32 s41, 0
	v_lshl_add_u64 v[88:89], v[86:87], 0, s[40:41]
	s_mov_b32 s40, 0xa01000
	v_lshl_add_u64 v[94:95], v[86:87], 0, s[40:41]
	global_load_dwordx4 v[160:163], v[88:89], off
	global_load_dwordx4 v[164:167], v[88:89], off offset:1024
	global_load_dwordx4 v[168:171], v[88:89], off offset:2048
	global_load_dwordx4 v[172:175], v[88:89], off offset:3072
	global_load_dwordx4 v[176:179], v[94:95], off
	global_load_dwordx4 v[180:183], v[94:95], off offset:1024
	global_load_dwordx4 v[184:187], v[94:95], off offset:2048
	global_load_dwordx4 v[188:191], v[94:95], off offset:3072
	s_mov_b32 s40, 0xb00000
	s_mov_b32 s41, 0
	v_lshl_add_u64 v[88:89], v[86:87], 0, s[40:41]
	s_mov_b32 s40, 0xb01000
	v_lshl_add_u64 v[94:95], v[86:87], 0, s[40:41]
	global_load_dwordx4 v[192:195], v[88:89], off
	global_load_dwordx4 v[196:199], v[88:89], off offset:1024
	global_load_dwordx4 v[200:203], v[88:89], off offset:2048
	global_load_dwordx4 v[204:207], v[88:89], off offset:3072
	global_load_dwordx4 v[208:211], v[94:95], off
	global_load_dwordx4 v[212:215], v[94:95], off offset:1024
	global_load_dwordx4 v[216:219], v[94:95], off offset:2048
	global_load_dwordx4 v[220:223], v[94:95], off offset:3072
	s_waitcnt vmcnt(31)
	v_pk_add_f32 v[82:83], v[82:83], v[96:97]
	v_pk_add_f32 v[80:81], v[80:81], v[98:99]
	s_waitcnt vmcnt(30)
	v_pk_add_f32 v[72:73], v[72:73], v[100:101]
	v_pk_add_f32 v[70:71], v[70:71], v[102:103]
	s_waitcnt vmcnt(29)
	v_pk_add_f32 v[84:85], v[84:85], v[104:105]
	v_pk_add_f32 v[20:21], v[20:21], v[106:107]
	s_waitcnt vmcnt(28)
	v_pk_add_f32 v[16:17], v[16:17], v[108:109]
	v_pk_add_f32 v[18:19], v[18:19], v[110:111]
	s_waitcnt vmcnt(27)
	v_pk_add_f32 v[12:13], v[12:13], v[112:113]
	v_pk_add_f32 v[14:15], v[14:15], v[114:115]
	s_waitcnt vmcnt(26)
	v_pk_add_f32 v[10:11], v[10:11], v[116:117]
	v_pk_add_f32 v[8:9], v[8:9], v[118:119]
	s_waitcnt vmcnt(25)
	v_pk_add_f32 v[0:1], v[0:1], v[120:121]
	v_pk_add_f32 v[2:3], v[2:3], v[122:123]
	s_waitcnt vmcnt(24)
	v_pk_add_f32 v[4:5], v[4:5], v[124:125]
	v_pk_add_f32 v[6:7], v[6:7], v[126:127]
	s_waitcnt vmcnt(23)
	v_pk_add_f32 v[82:83], v[82:83], v[128:129]
	v_pk_add_f32 v[80:81], v[80:81], v[130:131]
	s_waitcnt vmcnt(22)
	v_pk_add_f32 v[72:73], v[72:73], v[132:133]
	v_pk_add_f32 v[70:71], v[70:71], v[134:135]
	s_waitcnt vmcnt(21)
	v_pk_add_f32 v[84:85], v[84:85], v[136:137]
	v_pk_add_f32 v[20:21], v[20:21], v[138:139]
	s_waitcnt vmcnt(20)
	v_pk_add_f32 v[16:17], v[16:17], v[140:141]
	v_pk_add_f32 v[18:19], v[18:19], v[142:143]
	s_waitcnt vmcnt(19)
	v_pk_add_f32 v[12:13], v[12:13], v[144:145]
	v_pk_add_f32 v[14:15], v[14:15], v[146:147]
	s_waitcnt vmcnt(18)
	v_pk_add_f32 v[10:11], v[10:11], v[148:149]
	v_pk_add_f32 v[8:9], v[8:9], v[150:151]
	s_waitcnt vmcnt(17)
	v_pk_add_f32 v[0:1], v[0:1], v[152:153]
	v_pk_add_f32 v[2:3], v[2:3], v[154:155]
	s_waitcnt vmcnt(16)
	v_pk_add_f32 v[4:5], v[4:5], v[156:157]
	v_pk_add_f32 v[6:7], v[6:7], v[158:159]
	s_waitcnt vmcnt(15)
	v_pk_add_f32 v[82:83], v[82:83], v[160:161]
	v_pk_add_f32 v[80:81], v[80:81], v[162:163]
	s_waitcnt vmcnt(14)
	v_pk_add_f32 v[72:73], v[72:73], v[164:165]
	v_pk_add_f32 v[70:71], v[70:71], v[166:167]
	s_waitcnt vmcnt(13)
	v_pk_add_f32 v[84:85], v[84:85], v[168:169]
	v_pk_add_f32 v[20:21], v[20:21], v[170:171]
	s_waitcnt vmcnt(12)
	v_pk_add_f32 v[16:17], v[16:17], v[172:173]
	v_pk_add_f32 v[18:19], v[18:19], v[174:175]
	s_waitcnt vmcnt(11)
	v_pk_add_f32 v[12:13], v[12:13], v[176:177]
	v_pk_add_f32 v[14:15], v[14:15], v[178:179]
	s_waitcnt vmcnt(10)
	v_pk_add_f32 v[10:11], v[10:11], v[180:181]
	v_pk_add_f32 v[8:9], v[8:9], v[182:183]
	s_waitcnt vmcnt(9)
	v_pk_add_f32 v[0:1], v[0:1], v[184:185]
	v_pk_add_f32 v[2:3], v[2:3], v[186:187]
	s_waitcnt vmcnt(8)
	v_pk_add_f32 v[4:5], v[4:5], v[188:189]
	v_pk_add_f32 v[6:7], v[6:7], v[190:191]
	s_waitcnt vmcnt(7)
	v_pk_add_f32 v[82:83], v[82:83], v[192:193]
	v_pk_add_f32 v[80:81], v[80:81], v[194:195]
	s_waitcnt vmcnt(6)
	v_pk_add_f32 v[72:73], v[72:73], v[196:197]
	v_pk_add_f32 v[70:71], v[70:71], v[198:199]
	s_waitcnt vmcnt(5)
	v_pk_add_f32 v[84:85], v[84:85], v[200:201]
	v_pk_add_f32 v[20:21], v[20:21], v[202:203]
	s_waitcnt vmcnt(4)
	v_pk_add_f32 v[16:17], v[16:17], v[204:205]
	v_pk_add_f32 v[18:19], v[18:19], v[206:207]
	s_waitcnt vmcnt(3)
	v_pk_add_f32 v[12:13], v[12:13], v[208:209]
	v_pk_add_f32 v[14:15], v[14:15], v[210:211]
	s_waitcnt vmcnt(2)
	v_pk_add_f32 v[10:11], v[10:11], v[212:213]
	v_pk_add_f32 v[8:9], v[8:9], v[214:215]
	s_waitcnt vmcnt(1)
	v_pk_add_f32 v[0:1], v[0:1], v[216:217]
	v_pk_add_f32 v[2:3], v[2:3], v[218:219]
	s_waitcnt vmcnt(0)
	v_pk_add_f32 v[4:5], v[4:5], v[220:221]
	v_pk_add_f32 v[6:7], v[6:7], v[222:223]
	s_mov_b32 s40, 0xc00000
	s_mov_b32 s41, 0
	v_lshl_add_u64 v[88:89], v[86:87], 0, s[40:41]
	s_mov_b32 s40, 0xc01000
	v_lshl_add_u64 v[94:95], v[86:87], 0, s[40:41]
	global_load_dwordx4 v[96:99], v[88:89], off
	global_load_dwordx4 v[100:103], v[88:89], off offset:1024
	global_load_dwordx4 v[104:107], v[88:89], off offset:2048
	global_load_dwordx4 v[108:111], v[88:89], off offset:3072
	global_load_dwordx4 v[112:115], v[94:95], off
	global_load_dwordx4 v[116:119], v[94:95], off offset:1024
	global_load_dwordx4 v[120:123], v[94:95], off offset:2048
	global_load_dwordx4 v[124:127], v[94:95], off offset:3072
	s_mov_b32 s40, 0xd00000
	s_mov_b32 s41, 0
	v_lshl_add_u64 v[88:89], v[86:87], 0, s[40:41]
	s_mov_b32 s40, 0xd01000
	v_lshl_add_u64 v[94:95], v[86:87], 0, s[40:41]
	global_load_dwordx4 v[128:131], v[88:89], off
	global_load_dwordx4 v[132:135], v[88:89], off offset:1024
	global_load_dwordx4 v[136:139], v[88:89], off offset:2048
	global_load_dwordx4 v[140:143], v[88:89], off offset:3072
	global_load_dwordx4 v[144:147], v[94:95], off
	global_load_dwordx4 v[148:151], v[94:95], off offset:1024
	global_load_dwordx4 v[152:155], v[94:95], off offset:2048
	global_load_dwordx4 v[156:159], v[94:95], off offset:3072
	s_mov_b32 s40, 0xe00000
	s_mov_b32 s41, 0
	v_lshl_add_u64 v[88:89], v[86:87], 0, s[40:41]
	s_mov_b32 s40, 0xe01000
	v_lshl_add_u64 v[94:95], v[86:87], 0, s[40:41]
	global_load_dwordx4 v[160:163], v[88:89], off
	global_load_dwordx4 v[164:167], v[88:89], off offset:1024
	global_load_dwordx4 v[168:171], v[88:89], off offset:2048
	global_load_dwordx4 v[172:175], v[88:89], off offset:3072
	global_load_dwordx4 v[176:179], v[94:95], off
	global_load_dwordx4 v[180:183], v[94:95], off offset:1024
	global_load_dwordx4 v[184:187], v[94:95], off offset:2048
	global_load_dwordx4 v[188:191], v[94:95], off offset:3072
	s_mov_b32 s40, 0xf00000
	s_mov_b32 s41, 0
	v_lshl_add_u64 v[88:89], v[86:87], 0, s[40:41]
	s_mov_b32 s40, 0xf01000
	v_lshl_add_u64 v[94:95], v[86:87], 0, s[40:41]
	global_load_dwordx4 v[192:195], v[88:89], off
	global_load_dwordx4 v[196:199], v[88:89], off offset:1024
	global_load_dwordx4 v[200:203], v[88:89], off offset:2048
	global_load_dwordx4 v[204:207], v[88:89], off offset:3072
	global_load_dwordx4 v[208:211], v[94:95], off
	global_load_dwordx4 v[212:215], v[94:95], off offset:1024
	global_load_dwordx4 v[216:219], v[94:95], off offset:2048
	global_load_dwordx4 v[220:223], v[94:95], off offset:3072
	s_waitcnt vmcnt(31)
	v_pk_add_f32 v[82:83], v[82:83], v[96:97]
	v_pk_add_f32 v[80:81], v[80:81], v[98:99]
	s_waitcnt vmcnt(30)
	v_pk_add_f32 v[72:73], v[72:73], v[100:101]
	v_pk_add_f32 v[70:71], v[70:71], v[102:103]
	s_waitcnt vmcnt(29)
	v_pk_add_f32 v[84:85], v[84:85], v[104:105]
	v_pk_add_f32 v[20:21], v[20:21], v[106:107]
	s_waitcnt vmcnt(28)
	v_pk_add_f32 v[16:17], v[16:17], v[108:109]
	v_pk_add_f32 v[18:19], v[18:19], v[110:111]
	s_waitcnt vmcnt(27)
	v_pk_add_f32 v[12:13], v[12:13], v[112:113]
	v_pk_add_f32 v[14:15], v[14:15], v[114:115]
	s_waitcnt vmcnt(26)
	v_pk_add_f32 v[10:11], v[10:11], v[116:117]
	v_pk_add_f32 v[8:9], v[8:9], v[118:119]
	s_waitcnt vmcnt(25)
	v_pk_add_f32 v[0:1], v[0:1], v[120:121]
	v_pk_add_f32 v[2:3], v[2:3], v[122:123]
	s_waitcnt vmcnt(24)
	v_pk_add_f32 v[4:5], v[4:5], v[124:125]
	v_pk_add_f32 v[6:7], v[6:7], v[126:127]
	s_waitcnt vmcnt(23)
	v_pk_add_f32 v[82:83], v[82:83], v[128:129]
	v_pk_add_f32 v[80:81], v[80:81], v[130:131]
	s_waitcnt vmcnt(22)
	v_pk_add_f32 v[72:73], v[72:73], v[132:133]
	v_pk_add_f32 v[70:71], v[70:71], v[134:135]
	s_waitcnt vmcnt(21)
	v_pk_add_f32 v[84:85], v[84:85], v[136:137]
	v_pk_add_f32 v[20:21], v[20:21], v[138:139]
	s_waitcnt vmcnt(20)
	v_pk_add_f32 v[16:17], v[16:17], v[140:141]
	v_pk_add_f32 v[18:19], v[18:19], v[142:143]
	s_waitcnt vmcnt(19)
	v_pk_add_f32 v[12:13], v[12:13], v[144:145]
	v_pk_add_f32 v[14:15], v[14:15], v[146:147]
	s_waitcnt vmcnt(18)
	v_pk_add_f32 v[10:11], v[10:11], v[148:149]
	v_pk_add_f32 v[8:9], v[8:9], v[150:151]
	s_waitcnt vmcnt(17)
	v_pk_add_f32 v[0:1], v[0:1], v[152:153]
	v_pk_add_f32 v[2:3], v[2:3], v[154:155]
	s_waitcnt vmcnt(16)
	v_pk_add_f32 v[4:5], v[4:5], v[156:157]
	v_pk_add_f32 v[6:7], v[6:7], v[158:159]
	s_waitcnt vmcnt(15)
	v_pk_add_f32 v[82:83], v[82:83], v[160:161]
	v_pk_add_f32 v[80:81], v[80:81], v[162:163]
	s_waitcnt vmcnt(14)
	v_pk_add_f32 v[72:73], v[72:73], v[164:165]
	v_pk_add_f32 v[70:71], v[70:71], v[166:167]
	s_waitcnt vmcnt(13)
	v_pk_add_f32 v[84:85], v[84:85], v[168:169]
	v_pk_add_f32 v[20:21], v[20:21], v[170:171]
	s_waitcnt vmcnt(12)
	v_pk_add_f32 v[16:17], v[16:17], v[172:173]
	v_pk_add_f32 v[18:19], v[18:19], v[174:175]
	s_waitcnt vmcnt(11)
	v_pk_add_f32 v[12:13], v[12:13], v[176:177]
	v_pk_add_f32 v[14:15], v[14:15], v[178:179]
	s_waitcnt vmcnt(10)
	v_pk_add_f32 v[10:11], v[10:11], v[180:181]
	v_pk_add_f32 v[8:9], v[8:9], v[182:183]
	s_waitcnt vmcnt(9)
	v_pk_add_f32 v[0:1], v[0:1], v[184:185]
	v_pk_add_f32 v[2:3], v[2:3], v[186:187]
	s_waitcnt vmcnt(8)
	v_pk_add_f32 v[4:5], v[4:5], v[188:189]
	v_pk_add_f32 v[6:7], v[6:7], v[190:191]
	s_waitcnt vmcnt(7)
	v_pk_add_f32 v[82:83], v[82:83], v[192:193]
	v_pk_add_f32 v[80:81], v[80:81], v[194:195]
	s_waitcnt vmcnt(6)
	v_pk_add_f32 v[72:73], v[72:73], v[196:197]
	v_pk_add_f32 v[70:71], v[70:71], v[198:199]
	s_waitcnt vmcnt(5)
	v_pk_add_f32 v[84:85], v[84:85], v[200:201]
	v_pk_add_f32 v[20:21], v[20:21], v[202:203]
	s_waitcnt vmcnt(4)
	v_pk_add_f32 v[16:17], v[16:17], v[204:205]
	v_pk_add_f32 v[18:19], v[18:19], v[206:207]
	s_waitcnt vmcnt(3)
	v_pk_add_f32 v[12:13], v[12:13], v[208:209]
	v_pk_add_f32 v[14:15], v[14:15], v[210:211]
	s_waitcnt vmcnt(2)
	v_pk_add_f32 v[10:11], v[10:11], v[212:213]
	v_pk_add_f32 v[8:9], v[8:9], v[214:215]
	s_waitcnt vmcnt(1)
	v_pk_add_f32 v[0:1], v[0:1], v[216:217]
	v_pk_add_f32 v[2:3], v[2:3], v[218:219]
	s_waitcnt vmcnt(0)
	v_pk_add_f32 v[4:5], v[4:5], v[220:221]
	v_pk_add_f32 v[6:7], v[6:7], v[222:223]
	v_mov_b32_e32 v75, v8
	v_mov_b32_e32 v74, v11
	v_mov_b32_e32 v8, v10
	v_mov_b32_e32 v66, v15
	v_mov_b32_e32 v68, v13
	v_mov_b32_e32 v77, v20
	v_mov_b32_e32 v76, v85
	v_mov_b32_e32 v20, v84
	v_mov_b32_e32 v26, v71
	v_mov_b32_e32 v24, v73
	v_mov_b32_e32 v27, v81
	v_mov_b32_e32 v71, v80
	v_mov_b32_e32 v25, v83
	v_mov_b32_e32 v73, v82
